# phase-0 adaLN GEMV: weight-row loads of eight iterations kept in flight (loop unrolled x8 over a register ring); on top of previous best
# speedup vs baseline: 1.0043x; 1.0043x over previous
; __device__ __forceinline__ float silu_f(float x) { return x * fast_rcp(1.0f + __expf(-x)); }
; __device__ void phase_prep(const Params& p, LAS unsigned char* lds) {
;     ...
;             { float vv[18];
; #pragma unroll
;               for (int u = 0; u < 18; ++u) { const int i = tid + 512 * u, r = i >> 10, d = i & 1023; vv[u] = r < 8 ? p.in[1][r * 1024 + d] : p.in[3][d]; }
; #pragma unroll
;               for (int u = 0; u < 18; ++u) s[tid + 512 * u] = silu_f(vv[u]); }
;             __syncthreads();
;             const int l = job / 96, e0 = (job % 96) * 64, col = tid & 63, dg = tid >> 6;
;             const float* w = p.in[4] + ((size_t)l * 1024 + dg * 128) * 6144 + e0 + col;
;             float acc[9];
; #pragma unroll
;             for (int r = 0; r < 9; ++r) acc[r] = 0.f;
.LBB0_23:
	global_load_dword v52, v[46:47], off
	global_load_dword v53, v[14:15], off
	global_load_dword v54, v[16:17], off
	global_load_dword v55, v[18:19], off
	global_load_dword v56, v[20:21], off
	global_load_dword v57, v[22:23], off
	global_load_dword v58, v[24:25], off
	global_load_dword v59, v[26:27], off
	global_load_dword v60, v[28:29], off
	global_load_dword v61, v[30:31], off
	global_load_dword v64, v[32:33], off
	global_load_dword v65, v[34:35], off
	global_load_dword v66, v[36:37], off
	global_load_dword v67, v[38:39], off
	global_load_dword v68, v[40:41], off
	global_load_dword v69, v[42:43], off
	global_load_dword v70, v[44:45], off
	global_load_dword v71, v[48:49], off
	s_mul_hi_i32 s0, s33, 0x2aaaaaab
	s_lshr_b32 s16, s0, 31
	s_ashr_i32 s0, s0, 4
	s_add_i32 s18, s0, s16
	s_mul_i32 s0, s18, 0x60
	s_sub_i32 s0, s33, s0
	s_lshl_b32 s16, s0, 6
	s_ashr_i32 s19, s18, 31
	v_readlane_b32 s0, v244, 2
	s_lshl_b64 s[20:21], s[18:19], 10
	v_readlane_b32 s8, v244, 10
	v_readlane_b32 s9, v244, 11
	s_ashr_i32 s17, s16, 31
	v_readlane_b32 s1, v244, 3
	v_readlane_b32 s2, v244, 4
	v_readlane_b32 s3, v244, 5
	v_readlane_b32 s4, v244, 6
	v_readlane_b32 s5, v244, 7
	v_readlane_b32 s6, v244, 8
	v_readlane_b32 s7, v244, 9
	v_readlane_b32 s10, v244, 12
	v_readlane_b32 s11, v244, 13
	v_readlane_b32 s12, v244, 14
	v_readlane_b32 s13, v244, 15
	v_readlane_b32 s14, v244, 16
	v_readlane_b32 s15, v244, 17
	s_waitcnt vmcnt(17)
	v_mul_f32_e32 v72, 0xbfb8aa3b, v52
	s_waitcnt vmcnt(16)
	v_mul_f32_e32 v73, 0xbfb8aa3b, v53
	s_waitcnt vmcnt(15)
	v_mul_f32_e32 v74, 0xbfb8aa3b, v54
	s_waitcnt vmcnt(14)
	v_mul_f32_e32 v75, 0xbfb8aa3b, v55
	s_waitcnt vmcnt(13)
	v_mul_f32_e32 v76, 0xbfb8aa3b, v56
	s_waitcnt vmcnt(12)
	v_mul_f32_e32 v77, 0xbfb8aa3b, v57
	s_waitcnt vmcnt(11)
	v_mul_f32_e32 v78, 0xbfb8aa3b, v58
	s_waitcnt vmcnt(10)
	v_mul_f32_e32 v79, 0xbfb8aa3b, v59
	s_waitcnt vmcnt(9)
	v_mul_f32_e32 v80, 0xbfb8aa3b, v60
	s_waitcnt vmcnt(8)
	v_mul_f32_e32 v81, 0xbfb8aa3b, v61
	s_waitcnt vmcnt(7)
	v_mul_f32_e32 v82, 0xbfb8aa3b, v64
	s_waitcnt vmcnt(6)
	v_mul_f32_e32 v83, 0xbfb8aa3b, v65
	v_exp_f32_e32 v72, v72
	v_exp_f32_e32 v73, v73
	v_exp_f32_e32 v74, v74
	v_exp_f32_e32 v75, v75
	v_exp_f32_e32 v76, v76
	v_exp_f32_e32 v77, v77
	v_exp_f32_e32 v78, v78
	v_exp_f32_e32 v79, v79
	v_exp_f32_e32 v80, v80
	v_exp_f32_e32 v81, v81
	v_exp_f32_e32 v82, v82
	v_exp_f32_e32 v83, v83
	v_add_f32_e32 v72, 1.0, v72
	v_add_f32_e32 v73, 1.0, v73
	s_waitcnt vmcnt(5)
	v_mul_f32_e32 v84, 0xbfb8aa3b, v66
	s_waitcnt vmcnt(4)
	v_mul_f32_e32 v85, 0xbfb8aa3b, v67
	v_add_f32_e32 v74, 1.0, v74
	v_add_f32_e32 v75, 1.0, v75
	v_add_f32_e32 v76, 1.0, v76
	v_add_f32_e32 v77, 1.0, v77
	v_add_f32_e32 v78, 1.0, v78
	v_add_f32_e32 v79, 1.0, v79
	v_add_f32_e32 v80, 1.0, v80
	v_add_f32_e32 v81, 1.0, v81
	v_add_f32_e32 v82, 1.0, v82
	v_add_f32_e32 v83, 1.0, v83
	v_rcp_f32_e32 v72, v72
	v_rcp_f32_e32 v73, v73
	s_waitcnt vmcnt(3)
	v_mul_f32_e32 v86, 0xbfb8aa3b, v68
	v_exp_f32_e32 v84, v84
	v_exp_f32_e32 v85, v85
	v_rcp_f32_e32 v74, v74
	v_rcp_f32_e32 v75, v75
	v_rcp_f32_e32 v76, v76
	v_rcp_f32_e32 v77, v77
	v_rcp_f32_e32 v78, v78
	v_rcp_f32_e32 v79, v79
	v_rcp_f32_e32 v80, v80
	v_rcp_f32_e32 v81, v81
	v_rcp_f32_e32 v82, v82
	v_rcp_f32_e32 v83, v83
	v_exp_f32_e32 v86, v86
	v_mul_f32_e32 v52, v52, v72
	v_mul_f32_e32 v53, v53, v73
	v_add_f32_e32 v84, 1.0, v84
	v_mul_f32_e32 v54, v54, v74
	v_mul_f32_e32 v55, v55, v75
	v_mul_f32_e32 v56, v56, v76
	v_mul_f32_e32 v57, v57, v77
	v_mul_f32_e32 v58, v58, v78
	v_mul_f32_e32 v59, v59, v79
	v_mul_f32_e32 v60, v60, v80
	v_mul_f32_e32 v61, v61, v81
	v_mul_f32_e32 v64, v64, v82
	v_mul_f32_e32 v65, v65, v83
	ds_write2st64_b32 v1, v52, v53 offset1:8
	ds_write2st64_b32 v1, v54, v55 offset0:16 offset1:24
	ds_write2st64_b32 v1, v56, v57 offset0:32 offset1:40
	ds_write2st64_b32 v1, v58, v59 offset0:48 offset1:56
	ds_write2st64_b32 v1, v60, v61 offset0:64 offset1:72
	ds_write2st64_b32 v1, v64, v65 offset0:80 offset1:88
	v_add_f32_e32 v53, 1.0, v85
	v_rcp_f32_e32 v84, v84
	v_rcp_f32_e32 v53, v53
	v_add_f32_e32 v54, 1.0, v86
	s_waitcnt vmcnt(2)
	v_mul_f32_e32 v55, 0xbfb8aa3b, v69
	v_rcp_f32_e32 v54, v54
	v_exp_f32_e32 v55, v55
	v_mul_f32_e32 v52, v66, v84
	v_mul_f32_e32 v53, v67, v53
	ds_write2st64_b32 v1, v52, v53 offset0:96 offset1:104
	v_mul_f32_e32 v52, v68, v54
	v_add_f32_e32 v53, 1.0, v55
	s_waitcnt vmcnt(1)
	v_mul_f32_e32 v54, 0xbfb8aa3b, v70
	s_waitcnt vmcnt(0)
	v_mul_f32_e32 v55, 0xbfb8aa3b, v71
	v_exp_f32_e32 v54, v54
	v_exp_f32_e32 v55, v55
	v_rcp_f32_e32 v53, v53
	v_mov_b32_e32 v64, 0
	v_add_f32_e32 v54, 1.0, v54
	v_add_f32_e32 v55, 1.0, v55
	v_rcp_f32_e32 v54, v54
	v_rcp_f32_e32 v55, v55
	v_mul_f32_e32 v53, v69, v53
	ds_write2st64_b32 v1, v52, v53 offset0:112 offset1:120
	v_mul_f32_e32 v52, v70, v54
	v_mul_f32_e32 v53, v71, v55
	ds_write2st64_b32 v1, v52, v53 offset0:128 offset1:136
	v_lshl_add_u64 v[52:53], s[20:21], 0, v[8:9]
	v_mov_b64_e32 v[54:55], s[8:9]
	v_mad_u64_u32 v[54:55], s[20:21], v52, s29, v[54:55]
	v_mad_i32_i24 v55, v53, s29, v55
	v_lshl_add_u64 v[52:53], s[16:17], 2, v[54:55]
	v_lshlrev_b32_e32 v54, 2, v6
	v_mov_b32_e32 v55, v11
	v_lshl_add_u64 v[52:53], v[52:53], 0, v[54:55]
	s_mov_b64 s[20:21], 0
	v_mov_b32_e32 v65, v7
	v_mov_b32_e32 v54, 0
	v_mov_b32_e32 v55, v64
	v_mov_b32_e32 v56, 0
	v_mov_b32_e32 v57, v64
	v_mov_b32_e32 v58, 0
	v_mov_b32_e32 v59, v64
	v_mov_b32_e32 v60, 0
	v_mov_b32_e32 v61, v64
	s_waitcnt lgkmcnt(0)
	s_barrier
; __device__ void phase_prep(const Params& p, LAS unsigned char* lds) {
;     ...
;             for (int dd = 0; dd < 128; ++dd) { const float wv = w[(size_t)dd * 6144];
; #pragma unroll
;                 for (int r = 0; r < 9; ++r) acc[r] += s[r * 1024 + dg * 128 + dd] * wv; }
	s_mov_b32 s3, 0
	s_mov_b32 s5, 0
	s_mov_b32 s7, 0
	s_mov_b32 s11, 0
	s_mov_b32 s2, 0x0
	v_lshl_add_u64 v[204:205], v[52:53], 0, s[2:3]
	global_load_dword v140, v[204:205], off
	s_mov_b32 s4, 0x6000
	v_lshl_add_u64 v[206:207], v[52:53], 0, s[4:5]
	global_load_dword v142, v[206:207], off
	s_mov_b32 s6, 0xc000
	v_lshl_add_u64 v[208:209], v[52:53], 0, s[6:7]
	global_load_dword v144, v[208:209], off
	s_mov_b32 s10, 0x12000
	v_lshl_add_u64 v[210:211], v[52:53], 0, s[10:11]
	global_load_dword v146, v[210:211], off
	s_mov_b32 s2, 0x18000
	v_lshl_add_u64 v[204:205], v[52:53], 0, s[2:3]
	global_load_dword v148, v[204:205], off
	s_mov_b32 s4, 0x1e000
	v_lshl_add_u64 v[206:207], v[52:53], 0, s[4:5]
	global_load_dword v150, v[206:207], off
	s_mov_b32 s6, 0x24000
	v_lshl_add_u64 v[208:209], v[52:53], 0, s[6:7]
	global_load_dword v152, v[208:209], off
	s_mov_b32 s10, 0x2a000
	v_lshl_add_u64 v[210:211], v[52:53], 0, s[10:11]
	global_load_dword v154, v[210:211], off
	s_mov_b32 s2, 0x30000
	v_lshl_add_u64 v[204:205], v[52:53], 0, s[2:3]
	global_load_dword v156, v[204:205], off
	s_mov_b32 s4, 0x36000
	v_lshl_add_u64 v[206:207], v[52:53], 0, s[4:5]
	global_load_dword v158, v[206:207], off
	s_mov_b32 s6, 0x3c000
	v_lshl_add_u64 v[208:209], v[52:53], 0, s[6:7]
	global_load_dword v160, v[208:209], off
	s_mov_b32 s10, 0x42000
	v_lshl_add_u64 v[210:211], v[52:53], 0, s[10:11]
	global_load_dword v162, v[210:211], off
	s_mov_b32 s2, 0x48000
	v_lshl_add_u64 v[204:205], v[52:53], 0, s[2:3]
	global_load_dword v164, v[204:205], off
	s_mov_b32 s4, 0x4e000
	v_lshl_add_u64 v[206:207], v[52:53], 0, s[4:5]
	global_load_dword v166, v[206:207], off
	s_mov_b32 s6, 0x54000
	v_lshl_add_u64 v[208:209], v[52:53], 0, s[6:7]
	global_load_dword v168, v[208:209], off
	s_mov_b32 s10, 0x5a000
	v_lshl_add_u64 v[210:211], v[52:53], 0, s[10:11]
	global_load_dword v170, v[210:211], off
	s_mov_b32 s2, 0x60000
	v_lshl_add_u64 v[204:205], v[52:53], 0, s[2:3]
	global_load_dword v172, v[204:205], off
	s_mov_b32 s4, 0x66000
	v_lshl_add_u64 v[206:207], v[52:53], 0, s[4:5]
	global_load_dword v174, v[206:207], off
	s_mov_b32 s6, 0x6c000
	v_lshl_add_u64 v[208:209], v[52:53], 0, s[6:7]
	global_load_dword v176, v[208:209], off
	s_mov_b32 s10, 0x72000
	v_lshl_add_u64 v[210:211], v[52:53], 0, s[10:11]
	global_load_dword v178, v[210:211], off
	s_mov_b32 s2, 0x78000
	v_lshl_add_u64 v[204:205], v[52:53], 0, s[2:3]
	global_load_dword v180, v[204:205], off
	s_mov_b32 s4, 0x7e000
	v_lshl_add_u64 v[206:207], v[52:53], 0, s[4:5]
	global_load_dword v182, v[206:207], off
	s_mov_b32 s6, 0x84000
	v_lshl_add_u64 v[208:209], v[52:53], 0, s[6:7]
	global_load_dword v184, v[208:209], off
	s_mov_b32 s10, 0x8a000
	v_lshl_add_u64 v[210:211], v[52:53], 0, s[10:11]
	global_load_dword v186, v[210:211], off
	s_mov_b32 s2, 0x90000
	v_lshl_add_u64 v[204:205], v[52:53], 0, s[2:3]
	global_load_dword v188, v[204:205], off
	s_mov_b32 s4, 0x96000
	v_lshl_add_u64 v[206:207], v[52:53], 0, s[4:5]
	global_load_dword v190, v[206:207], off
	s_mov_b32 s6, 0x9c000
	v_lshl_add_u64 v[208:209], v[52:53], 0, s[6:7]
	global_load_dword v192, v[208:209], off
	s_mov_b32 s10, 0xa2000
	v_lshl_add_u64 v[210:211], v[52:53], 0, s[10:11]
	global_load_dword v194, v[210:211], off
	s_mov_b32 s2, 0xa8000
	v_lshl_add_u64 v[204:205], v[52:53], 0, s[2:3]
	global_load_dword v196, v[204:205], off
	s_mov_b32 s4, 0xae000
	v_lshl_add_u64 v[206:207], v[52:53], 0, s[4:5]
	global_load_dword v198, v[206:207], off
	s_mov_b32 s6, 0xb4000
	v_lshl_add_u64 v[208:209], v[52:53], 0, s[6:7]
	global_load_dword v200, v[208:209], off
	s_mov_b32 s10, 0xba000
	v_lshl_add_u64 v[210:211], v[52:53], 0, s[10:11]
	global_load_dword v202, v[210:211], off
.LBB0_24:
	s_add_u32 s20, s20, 0x18000
	s_addc_u32 s21, s21, 0
	ds_read_b128 v[66:69], v65 offset:4096
	ds_read_b128 v[70:73], v65 offset:8192
	ds_read_b128 v[74:77], v65 offset:12288
	ds_read_b128 v[78:81], v65 offset:16384
	ds_read_b128 v[82:85], v65 offset:20480
	ds_read_b128 v[86:89], v65 offset:24576
	ds_read_b128 v[90:93], v65 offset:28672
	ds_read_b128 v[94:97], v65
	ds_read_b128 v[98:101], v65 offset:32768
	s_waitcnt lgkmcnt(7)
	v_mov_b32_e32 v110, v70
	v_mov_b32_e32 v111, v66
	s_waitcnt lgkmcnt(5)
	v_mov_b32_e32 v112, v78
	v_mov_b32_e32 v113, v74
	s_waitcnt lgkmcnt(3)
	v_mov_b32_e32 v114, v86
	v_mov_b32_e32 v115, v82
	s_waitcnt lgkmcnt(0)
	v_mov_b32_e32 v116, v98
	v_mov_b32_e32 v117, v90
	v_mov_b32_e32 v66, v71
	v_mov_b32_e32 v74, v79
	v_mov_b32_e32 v82, v87
	v_mov_b32_e32 v90, v99
	v_mov_b32_e32 v70, v72
	v_mov_b32_e32 v71, v68
	v_mov_b32_e32 v78, v80
	v_mov_b32_e32 v79, v76
	v_mov_b32_e32 v68, v73
	v_mov_b32_e32 v72, v88
	v_mov_b32_e32 v73, v84
	v_mov_b32_e32 v86, v100
	v_mov_b32_e32 v87, v92
	v_mov_b32_e32 v76, v81
	v_mov_b32_e32 v84, v89
	v_mov_b32_e32 v92, v101
	v_add_u32_e32 v65, 16, v65
	s_waitcnt vmcnt(28)
; __device__ void phase_prep(const Params& p, LAS unsigned char* lds) {
;     ...
;             for (int dd = 0; dd < 128; ++dd) { const float wv = w[(size_t)dd * 6144];
; #pragma unroll
;                 for (int r = 0; r < 9; ++r) acc[r] += s[r * 1024 + dg * 128 + dd] * wv; }
	v_fmac_f32_e32 v64, v140, v94
	v_pk_fma_f32 v[60:61], v[140:141], v[110:111], v[60:61] op_sel_hi:[0,1,1]
	v_pk_fma_f32 v[58:59], v[140:141], v[112:113], v[58:59] op_sel_hi:[0,1,1]
	v_pk_fma_f32 v[56:57], v[140:141], v[114:115], v[56:57] op_sel_hi:[0,1,1]
	v_pk_fma_f32 v[54:55], v[140:141], v[116:117], v[54:55] op_sel_hi:[0,1,1]
	v_fmac_f32_e32 v64, v142, v95
	v_pk_fma_f32 v[60:61], v[142:143], v[66:67], v[60:61] op_sel_hi:[0,1,1]
	v_pk_fma_f32 v[58:59], v[142:143], v[74:75], v[58:59] op_sel_hi:[0,1,1]
	v_pk_fma_f32 v[56:57], v[142:143], v[82:83], v[56:57] op_sel_hi:[0,1,1]
	v_pk_fma_f32 v[54:55], v[142:143], v[90:91], v[54:55] op_sel_hi:[0,1,1]
	v_fmac_f32_e32 v64, v144, v96
	v_pk_fma_f32 v[60:61], v[144:145], v[70:71], v[60:61] op_sel_hi:[0,1,1]
	v_pk_fma_f32 v[58:59], v[144:145], v[78:79], v[58:59] op_sel_hi:[0,1,1]
	v_pk_fma_f32 v[56:57], v[144:145], v[72:73], v[56:57] op_sel_hi:[0,1,1]
	v_pk_fma_f32 v[54:55], v[144:145], v[86:87], v[54:55] op_sel_hi:[0,1,1]
	v_fmac_f32_e32 v64, v146, v97
	v_pk_fma_f32 v[60:61], v[146:147], v[68:69], v[60:61] op_sel_hi:[0,1,1]
	v_pk_fma_f32 v[58:59], v[146:147], v[76:77], v[58:59] op_sel_hi:[0,1,1]
	v_pk_fma_f32 v[56:57], v[146:147], v[84:85], v[56:57] op_sel_hi:[0,1,1]
	v_pk_fma_f32 v[54:55], v[146:147], v[92:93], v[54:55] op_sel_hi:[0,1,1]
	s_add_u32 s2, s20, 0xa8000
	s_min_u32 s2, s2, 0x2e8000
	s_add_u32 s4, s2, 0x6000
	s_add_u32 s6, s2, 0xc000
	s_add_u32 s10, s2, 0x12000
	v_lshl_add_u64 v[204:205], v[52:53], 0, s[2:3]
	global_load_dword v140, v[204:205], off
	v_lshl_add_u64 v[206:207], v[52:53], 0, s[4:5]
	global_load_dword v142, v[206:207], off
	v_lshl_add_u64 v[208:209], v[52:53], 0, s[6:7]
	global_load_dword v144, v[208:209], off
	v_lshl_add_u64 v[210:211], v[52:53], 0, s[10:11]
	global_load_dword v146, v[210:211], off
	s_add_u32 s20, s20, 0x18000
	s_addc_u32 s21, s21, 0
	ds_read_b128 v[66:69], v65 offset:4096
	ds_read_b128 v[70:73], v65 offset:8192
	ds_read_b128 v[74:77], v65 offset:12288
	ds_read_b128 v[78:81], v65 offset:16384
	ds_read_b128 v[82:85], v65 offset:20480
	ds_read_b128 v[86:89], v65 offset:24576
	ds_read_b128 v[90:93], v65 offset:28672
	ds_read_b128 v[94:97], v65
	ds_read_b128 v[98:101], v65 offset:32768
	s_waitcnt lgkmcnt(7)
	v_mov_b32_e32 v110, v70
	v_mov_b32_e32 v111, v66
	s_waitcnt lgkmcnt(5)
	v_mov_b32_e32 v112, v78
	v_mov_b32_e32 v113, v74
	s_waitcnt lgkmcnt(3)
	v_mov_b32_e32 v114, v86
	v_mov_b32_e32 v115, v82
	s_waitcnt lgkmcnt(0)
	v_mov_b32_e32 v116, v98
	v_mov_b32_e32 v117, v90
	v_mov_b32_e32 v66, v71
	v_mov_b32_e32 v74, v79
	v_mov_b32_e32 v82, v87
	v_mov_b32_e32 v90, v99
	v_mov_b32_e32 v70, v72
	v_mov_b32_e32 v71, v68
	v_mov_b32_e32 v78, v80
	v_mov_b32_e32 v79, v76
	v_mov_b32_e32 v68, v73
	v_mov_b32_e32 v72, v88
	v_mov_b32_e32 v73, v84
	v_mov_b32_e32 v86, v100
	v_mov_b32_e32 v87, v92
	v_mov_b32_e32 v76, v81
	v_mov_b32_e32 v84, v89
	v_mov_b32_e32 v92, v101
	v_add_u32_e32 v65, 16, v65
	s_waitcnt vmcnt(28)
	v_fmac_f32_e32 v64, v148, v94
	v_pk_fma_f32 v[60:61], v[148:149], v[110:111], v[60:61] op_sel_hi:[0,1,1]
	v_pk_fma_f32 v[58:59], v[148:149], v[112:113], v[58:59] op_sel_hi:[0,1,1]
	v_pk_fma_f32 v[56:57], v[148:149], v[114:115], v[56:57] op_sel_hi:[0,1,1]
	v_pk_fma_f32 v[54:55], v[148:149], v[116:117], v[54:55] op_sel_hi:[0,1,1]
	v_fmac_f32_e32 v64, v150, v95
	v_pk_fma_f32 v[60:61], v[150:151], v[66:67], v[60:61] op_sel_hi:[0,1,1]
	v_pk_fma_f32 v[58:59], v[150:151], v[74:75], v[58:59] op_sel_hi:[0,1,1]
	v_pk_fma_f32 v[56:57], v[150:151], v[82:83], v[56:57] op_sel_hi:[0,1,1]
	v_pk_fma_f32 v[54:55], v[150:151], v[90:91], v[54:55] op_sel_hi:[0,1,1]
	v_fmac_f32_e32 v64, v152, v96
	v_pk_fma_f32 v[60:61], v[152:153], v[70:71], v[60:61] op_sel_hi:[0,1,1]
	v_pk_fma_f32 v[58:59], v[152:153], v[78:79], v[58:59] op_sel_hi:[0,1,1]
	v_pk_fma_f32 v[56:57], v[152:153], v[72:73], v[56:57] op_sel_hi:[0,1,1]
	v_pk_fma_f32 v[54:55], v[152:153], v[86:87], v[54:55] op_sel_hi:[0,1,1]
	v_fmac_f32_e32 v64, v154, v97
	v_pk_fma_f32 v[60:61], v[154:155], v[68:69], v[60:61] op_sel_hi:[0,1,1]
	v_pk_fma_f32 v[58:59], v[154:155], v[76:77], v[58:59] op_sel_hi:[0,1,1]
	v_pk_fma_f32 v[56:57], v[154:155], v[84:85], v[56:57] op_sel_hi:[0,1,1]
	v_pk_fma_f32 v[54:55], v[154:155], v[92:93], v[54:55] op_sel_hi:[0,1,1]
	s_add_u32 s2, s20, 0xa8000
	s_min_u32 s2, s2, 0x2e8000
	s_add_u32 s4, s2, 0x6000
	s_add_u32 s6, s2, 0xc000
	s_add_u32 s10, s2, 0x12000
	v_lshl_add_u64 v[204:205], v[52:53], 0, s[2:3]
	global_load_dword v148, v[204:205], off
	v_lshl_add_u64 v[206:207], v[52:53], 0, s[4:5]
	global_load_dword v150, v[206:207], off
	v_lshl_add_u64 v[208:209], v[52:53], 0, s[6:7]
	global_load_dword v152, v[208:209], off
	v_lshl_add_u64 v[210:211], v[52:53], 0, s[10:11]
	global_load_dword v154, v[210:211], off
	s_add_u32 s20, s20, 0x18000
	s_addc_u32 s21, s21, 0
	ds_read_b128 v[66:69], v65 offset:4096
	ds_read_b128 v[70:73], v65 offset:8192
	ds_read_b128 v[74:77], v65 offset:12288
	ds_read_b128 v[78:81], v65 offset:16384
	ds_read_b128 v[82:85], v65 offset:20480
	ds_read_b128 v[86:89], v65 offset:24576
	ds_read_b128 v[90:93], v65 offset:28672
	ds_read_b128 v[94:97], v65
	ds_read_b128 v[98:101], v65 offset:32768
	s_waitcnt lgkmcnt(7)
	v_mov_b32_e32 v110, v70
	v_mov_b32_e32 v111, v66
	s_waitcnt lgkmcnt(5)
	v_mov_b32_e32 v112, v78
	v_mov_b32_e32 v113, v74
	s_waitcnt lgkmcnt(3)
	v_mov_b32_e32 v114, v86
	v_mov_b32_e32 v115, v82
	s_waitcnt lgkmcnt(0)
	v_mov_b32_e32 v116, v98
	v_mov_b32_e32 v117, v90
	v_mov_b32_e32 v66, v71
	v_mov_b32_e32 v74, v79
	v_mov_b32_e32 v82, v87
	v_mov_b32_e32 v90, v99
	v_mov_b32_e32 v70, v72
	v_mov_b32_e32 v71, v68
	v_mov_b32_e32 v78, v80
	v_mov_b32_e32 v79, v76
	v_mov_b32_e32 v68, v73
	v_mov_b32_e32 v72, v88
	v_mov_b32_e32 v73, v84
	v_mov_b32_e32 v86, v100
	v_mov_b32_e32 v87, v92
	v_mov_b32_e32 v76, v81
	v_mov_b32_e32 v84, v89
	v_mov_b32_e32 v92, v101
	v_add_u32_e32 v65, 16, v65
	s_waitcnt vmcnt(28)
; __device__ void phase_prep(const Params& p, LAS unsigned char* lds) {
;     ...
;             for (int dd = 0; dd < 128; ++dd) { const float wv = w[(size_t)dd * 6144];
; #pragma unroll
;                 for (int r = 0; r < 9; ++r) acc[r] += s[r * 1024 + dg * 128 + dd] * wv; }
	v_fmac_f32_e32 v64, v156, v94
	v_pk_fma_f32 v[60:61], v[156:157], v[110:111], v[60:61] op_sel_hi:[0,1,1]
	v_pk_fma_f32 v[58:59], v[156:157], v[112:113], v[58:59] op_sel_hi:[0,1,1]
	v_pk_fma_f32 v[56:57], v[156:157], v[114:115], v[56:57] op_sel_hi:[0,1,1]
	v_pk_fma_f32 v[54:55], v[156:157], v[116:117], v[54:55] op_sel_hi:[0,1,1]
	v_fmac_f32_e32 v64, v158, v95
	v_pk_fma_f32 v[60:61], v[158:159], v[66:67], v[60:61] op_sel_hi:[0,1,1]
	v_pk_fma_f32 v[58:59], v[158:159], v[74:75], v[58:59] op_sel_hi:[0,1,1]
	v_pk_fma_f32 v[56:57], v[158:159], v[82:83], v[56:57] op_sel_hi:[0,1,1]
	v_pk_fma_f32 v[54:55], v[158:159], v[90:91], v[54:55] op_sel_hi:[0,1,1]
	v_fmac_f32_e32 v64, v160, v96
	v_pk_fma_f32 v[60:61], v[160:161], v[70:71], v[60:61] op_sel_hi:[0,1,1]
	v_pk_fma_f32 v[58:59], v[160:161], v[78:79], v[58:59] op_sel_hi:[0,1,1]
	v_pk_fma_f32 v[56:57], v[160:161], v[72:73], v[56:57] op_sel_hi:[0,1,1]
	v_pk_fma_f32 v[54:55], v[160:161], v[86:87], v[54:55] op_sel_hi:[0,1,1]
	v_fmac_f32_e32 v64, v162, v97
	v_pk_fma_f32 v[60:61], v[162:163], v[68:69], v[60:61] op_sel_hi:[0,1,1]
	v_pk_fma_f32 v[58:59], v[162:163], v[76:77], v[58:59] op_sel_hi:[0,1,1]
	v_pk_fma_f32 v[56:57], v[162:163], v[84:85], v[56:57] op_sel_hi:[0,1,1]
	v_pk_fma_f32 v[54:55], v[162:163], v[92:93], v[54:55] op_sel_hi:[0,1,1]
	s_add_u32 s2, s20, 0xa8000
	s_min_u32 s2, s2, 0x2e8000
	s_add_u32 s4, s2, 0x6000
	s_add_u32 s6, s2, 0xc000
	s_add_u32 s10, s2, 0x12000
	v_lshl_add_u64 v[204:205], v[52:53], 0, s[2:3]
	global_load_dword v156, v[204:205], off
	v_lshl_add_u64 v[206:207], v[52:53], 0, s[4:5]
	global_load_dword v158, v[206:207], off
	v_lshl_add_u64 v[208:209], v[52:53], 0, s[6:7]
	global_load_dword v160, v[208:209], off
	v_lshl_add_u64 v[210:211], v[52:53], 0, s[10:11]
	global_load_dword v162, v[210:211], off
	s_add_u32 s20, s20, 0x18000
	s_addc_u32 s21, s21, 0
	ds_read_b128 v[66:69], v65 offset:4096
	ds_read_b128 v[70:73], v65 offset:8192
	ds_read_b128 v[74:77], v65 offset:12288
	ds_read_b128 v[78:81], v65 offset:16384
	ds_read_b128 v[82:85], v65 offset:20480
	ds_read_b128 v[86:89], v65 offset:24576
	ds_read_b128 v[90:93], v65 offset:28672
	ds_read_b128 v[94:97], v65
	ds_read_b128 v[98:101], v65 offset:32768
	s_waitcnt lgkmcnt(7)
	v_mov_b32_e32 v110, v70
	v_mov_b32_e32 v111, v66
	s_waitcnt lgkmcnt(5)
	v_mov_b32_e32 v112, v78
	v_mov_b32_e32 v113, v74
	s_waitcnt lgkmcnt(3)
	v_mov_b32_e32 v114, v86
	v_mov_b32_e32 v115, v82
	s_waitcnt lgkmcnt(0)
	v_mov_b32_e32 v116, v98
	v_mov_b32_e32 v117, v90
	v_mov_b32_e32 v66, v71
	v_mov_b32_e32 v74, v79
	v_mov_b32_e32 v82, v87
	v_mov_b32_e32 v90, v99
	v_mov_b32_e32 v70, v72
	v_mov_b32_e32 v71, v68
	v_mov_b32_e32 v78, v80
	v_mov_b32_e32 v79, v76
	v_mov_b32_e32 v68, v73
	v_mov_b32_e32 v72, v88
	v_mov_b32_e32 v73, v84
	v_mov_b32_e32 v86, v100
	v_mov_b32_e32 v87, v92
	v_mov_b32_e32 v76, v81
	v_mov_b32_e32 v84, v89
	v_mov_b32_e32 v92, v101
	v_add_u32_e32 v65, 16, v65
	s_waitcnt vmcnt(28)
	v_fmac_f32_e32 v64, v164, v94
	v_pk_fma_f32 v[60:61], v[164:165], v[110:111], v[60:61] op_sel_hi:[0,1,1]
	v_pk_fma_f32 v[58:59], v[164:165], v[112:113], v[58:59] op_sel_hi:[0,1,1]
	v_pk_fma_f32 v[56:57], v[164:165], v[114:115], v[56:57] op_sel_hi:[0,1,1]
	v_pk_fma_f32 v[54:55], v[164:165], v[116:117], v[54:55] op_sel_hi:[0,1,1]
	v_fmac_f32_e32 v64, v166, v95
	v_pk_fma_f32 v[60:61], v[166:167], v[66:67], v[60:61] op_sel_hi:[0,1,1]
	v_pk_fma_f32 v[58:59], v[166:167], v[74:75], v[58:59] op_sel_hi:[0,1,1]
	v_pk_fma_f32 v[56:57], v[166:167], v[82:83], v[56:57] op_sel_hi:[0,1,1]
	v_pk_fma_f32 v[54:55], v[166:167], v[90:91], v[54:55] op_sel_hi:[0,1,1]
	v_fmac_f32_e32 v64, v168, v96
	v_pk_fma_f32 v[60:61], v[168:169], v[70:71], v[60:61] op_sel_hi:[0,1,1]
	v_pk_fma_f32 v[58:59], v[168:169], v[78:79], v[58:59] op_sel_hi:[0,1,1]
	v_pk_fma_f32 v[56:57], v[168:169], v[72:73], v[56:57] op_sel_hi:[0,1,1]
	v_pk_fma_f32 v[54:55], v[168:169], v[86:87], v[54:55] op_sel_hi:[0,1,1]
	v_fmac_f32_e32 v64, v170, v97
	v_pk_fma_f32 v[60:61], v[170:171], v[68:69], v[60:61] op_sel_hi:[0,1,1]
	v_pk_fma_f32 v[58:59], v[170:171], v[76:77], v[58:59] op_sel_hi:[0,1,1]
	v_pk_fma_f32 v[56:57], v[170:171], v[84:85], v[56:57] op_sel_hi:[0,1,1]
	v_pk_fma_f32 v[54:55], v[170:171], v[92:93], v[54:55] op_sel_hi:[0,1,1]
	s_add_u32 s2, s20, 0xa8000
	s_min_u32 s2, s2, 0x2e8000
	s_add_u32 s4, s2, 0x6000
	s_add_u32 s6, s2, 0xc000
	s_add_u32 s10, s2, 0x12000
	v_lshl_add_u64 v[204:205], v[52:53], 0, s[2:3]
	global_load_dword v164, v[204:205], off
	v_lshl_add_u64 v[206:207], v[52:53], 0, s[4:5]
	global_load_dword v166, v[206:207], off
	v_lshl_add_u64 v[208:209], v[52:53], 0, s[6:7]
	global_load_dword v168, v[208:209], off
	v_lshl_add_u64 v[210:211], v[52:53], 0, s[10:11]
	global_load_dword v170, v[210:211], off
	s_add_u32 s20, s20, 0x18000
	s_addc_u32 s21, s21, 0
	ds_read_b128 v[66:69], v65 offset:4096
	ds_read_b128 v[70:73], v65 offset:8192
	ds_read_b128 v[74:77], v65 offset:12288
	ds_read_b128 v[78:81], v65 offset:16384
	ds_read_b128 v[82:85], v65 offset:20480
	ds_read_b128 v[86:89], v65 offset:24576
	ds_read_b128 v[90:93], v65 offset:28672
	ds_read_b128 v[94:97], v65
	ds_read_b128 v[98:101], v65 offset:32768
	s_waitcnt lgkmcnt(7)
	v_mov_b32_e32 v110, v70
	v_mov_b32_e32 v111, v66
	s_waitcnt lgkmcnt(5)
	v_mov_b32_e32 v112, v78
	v_mov_b32_e32 v113, v74
	s_waitcnt lgkmcnt(3)
	v_mov_b32_e32 v114, v86
	v_mov_b32_e32 v115, v82
	s_waitcnt lgkmcnt(0)
	v_mov_b32_e32 v116, v98
	v_mov_b32_e32 v117, v90
	v_mov_b32_e32 v66, v71
	v_mov_b32_e32 v74, v79
	v_mov_b32_e32 v82, v87
	v_mov_b32_e32 v90, v99
	v_mov_b32_e32 v70, v72
	v_mov_b32_e32 v71, v68
	v_mov_b32_e32 v78, v80
	v_mov_b32_e32 v79, v76
	v_mov_b32_e32 v68, v73
	v_mov_b32_e32 v72, v88
	v_mov_b32_e32 v73, v84
	v_mov_b32_e32 v86, v100
	v_mov_b32_e32 v87, v92
	v_mov_b32_e32 v76, v81
	v_mov_b32_e32 v84, v89
	v_mov_b32_e32 v92, v101
	v_add_u32_e32 v65, 16, v65
	s_waitcnt vmcnt(28)
; __device__ void phase_prep(const Params& p, LAS unsigned char* lds) {
;     ...
;             for (int dd = 0; dd < 128; ++dd) { const float wv = w[(size_t)dd * 6144];
; #pragma unroll
;                 for (int r = 0; r < 9; ++r) acc[r] += s[r * 1024 + dg * 128 + dd] * wv; }
	v_fmac_f32_e32 v64, v172, v94
	v_pk_fma_f32 v[60:61], v[172:173], v[110:111], v[60:61] op_sel_hi:[0,1,1]
	v_pk_fma_f32 v[58:59], v[172:173], v[112:113], v[58:59] op_sel_hi:[0,1,1]
	v_pk_fma_f32 v[56:57], v[172:173], v[114:115], v[56:57] op_sel_hi:[0,1,1]
	v_pk_fma_f32 v[54:55], v[172:173], v[116:117], v[54:55] op_sel_hi:[0,1,1]
	v_fmac_f32_e32 v64, v174, v95
	v_pk_fma_f32 v[60:61], v[174:175], v[66:67], v[60:61] op_sel_hi:[0,1,1]
	v_pk_fma_f32 v[58:59], v[174:175], v[74:75], v[58:59] op_sel_hi:[0,1,1]
	v_pk_fma_f32 v[56:57], v[174:175], v[82:83], v[56:57] op_sel_hi:[0,1,1]
	v_pk_fma_f32 v[54:55], v[174:175], v[90:91], v[54:55] op_sel_hi:[0,1,1]
	v_fmac_f32_e32 v64, v176, v96
	v_pk_fma_f32 v[60:61], v[176:177], v[70:71], v[60:61] op_sel_hi:[0,1,1]
	v_pk_fma_f32 v[58:59], v[176:177], v[78:79], v[58:59] op_sel_hi:[0,1,1]
	v_pk_fma_f32 v[56:57], v[176:177], v[72:73], v[56:57] op_sel_hi:[0,1,1]
	v_pk_fma_f32 v[54:55], v[176:177], v[86:87], v[54:55] op_sel_hi:[0,1,1]
	v_fmac_f32_e32 v64, v178, v97
	v_pk_fma_f32 v[60:61], v[178:179], v[68:69], v[60:61] op_sel_hi:[0,1,1]
	v_pk_fma_f32 v[58:59], v[178:179], v[76:77], v[58:59] op_sel_hi:[0,1,1]
	v_pk_fma_f32 v[56:57], v[178:179], v[84:85], v[56:57] op_sel_hi:[0,1,1]
	v_pk_fma_f32 v[54:55], v[178:179], v[92:93], v[54:55] op_sel_hi:[0,1,1]
	s_add_u32 s2, s20, 0xa8000
	s_min_u32 s2, s2, 0x2e8000
	s_add_u32 s4, s2, 0x6000
	s_add_u32 s6, s2, 0xc000
	s_add_u32 s10, s2, 0x12000
	v_lshl_add_u64 v[204:205], v[52:53], 0, s[2:3]
	global_load_dword v172, v[204:205], off
	v_lshl_add_u64 v[206:207], v[52:53], 0, s[4:5]
	global_load_dword v174, v[206:207], off
	v_lshl_add_u64 v[208:209], v[52:53], 0, s[6:7]
	global_load_dword v176, v[208:209], off
	v_lshl_add_u64 v[210:211], v[52:53], 0, s[10:11]
	global_load_dword v178, v[210:211], off
	s_add_u32 s20, s20, 0x18000
	s_addc_u32 s21, s21, 0
	ds_read_b128 v[66:69], v65 offset:4096
	ds_read_b128 v[70:73], v65 offset:8192
	ds_read_b128 v[74:77], v65 offset:12288
	ds_read_b128 v[78:81], v65 offset:16384
	ds_read_b128 v[82:85], v65 offset:20480
	ds_read_b128 v[86:89], v65 offset:24576
	ds_read_b128 v[90:93], v65 offset:28672
	ds_read_b128 v[94:97], v65
	ds_read_b128 v[98:101], v65 offset:32768
	s_waitcnt lgkmcnt(7)
	v_mov_b32_e32 v110, v70
	v_mov_b32_e32 v111, v66
	s_waitcnt lgkmcnt(5)
	v_mov_b32_e32 v112, v78
	v_mov_b32_e32 v113, v74
	s_waitcnt lgkmcnt(3)
	v_mov_b32_e32 v114, v86
	v_mov_b32_e32 v115, v82
	s_waitcnt lgkmcnt(0)
	v_mov_b32_e32 v116, v98
	v_mov_b32_e32 v117, v90
	v_mov_b32_e32 v66, v71
	v_mov_b32_e32 v74, v79
	v_mov_b32_e32 v82, v87
	v_mov_b32_e32 v90, v99
	v_mov_b32_e32 v70, v72
	v_mov_b32_e32 v71, v68
	v_mov_b32_e32 v78, v80
	v_mov_b32_e32 v79, v76
	v_mov_b32_e32 v68, v73
	v_mov_b32_e32 v72, v88
	v_mov_b32_e32 v73, v84
	v_mov_b32_e32 v86, v100
	v_mov_b32_e32 v87, v92
	v_mov_b32_e32 v76, v81
	v_mov_b32_e32 v84, v89
	v_mov_b32_e32 v92, v101
	v_add_u32_e32 v65, 16, v65
	s_waitcnt vmcnt(28)
	v_fmac_f32_e32 v64, v180, v94
	v_pk_fma_f32 v[60:61], v[180:181], v[110:111], v[60:61] op_sel_hi:[0,1,1]
	v_pk_fma_f32 v[58:59], v[180:181], v[112:113], v[58:59] op_sel_hi:[0,1,1]
	v_pk_fma_f32 v[56:57], v[180:181], v[114:115], v[56:57] op_sel_hi:[0,1,1]
	v_pk_fma_f32 v[54:55], v[180:181], v[116:117], v[54:55] op_sel_hi:[0,1,1]
	v_fmac_f32_e32 v64, v182, v95
	v_pk_fma_f32 v[60:61], v[182:183], v[66:67], v[60:61] op_sel_hi:[0,1,1]
	v_pk_fma_f32 v[58:59], v[182:183], v[74:75], v[58:59] op_sel_hi:[0,1,1]
	v_pk_fma_f32 v[56:57], v[182:183], v[82:83], v[56:57] op_sel_hi:[0,1,1]
	v_pk_fma_f32 v[54:55], v[182:183], v[90:91], v[54:55] op_sel_hi:[0,1,1]
	v_fmac_f32_e32 v64, v184, v96
	v_pk_fma_f32 v[60:61], v[184:185], v[70:71], v[60:61] op_sel_hi:[0,1,1]
	v_pk_fma_f32 v[58:59], v[184:185], v[78:79], v[58:59] op_sel_hi:[0,1,1]
	v_pk_fma_f32 v[56:57], v[184:185], v[72:73], v[56:57] op_sel_hi:[0,1,1]
	v_pk_fma_f32 v[54:55], v[184:185], v[86:87], v[54:55] op_sel_hi:[0,1,1]
	v_fmac_f32_e32 v64, v186, v97
	v_pk_fma_f32 v[60:61], v[186:187], v[68:69], v[60:61] op_sel_hi:[0,1,1]
	v_pk_fma_f32 v[58:59], v[186:187], v[76:77], v[58:59] op_sel_hi:[0,1,1]
	v_pk_fma_f32 v[56:57], v[186:187], v[84:85], v[56:57] op_sel_hi:[0,1,1]
	v_pk_fma_f32 v[54:55], v[186:187], v[92:93], v[54:55] op_sel_hi:[0,1,1]
	s_add_u32 s2, s20, 0xa8000
	s_min_u32 s2, s2, 0x2e8000
	s_add_u32 s4, s2, 0x6000
	s_add_u32 s6, s2, 0xc000
	s_add_u32 s10, s2, 0x12000
	v_lshl_add_u64 v[204:205], v[52:53], 0, s[2:3]
	global_load_dword v180, v[204:205], off
	v_lshl_add_u64 v[206:207], v[52:53], 0, s[4:5]
	global_load_dword v182, v[206:207], off
	v_lshl_add_u64 v[208:209], v[52:53], 0, s[6:7]
	global_load_dword v184, v[208:209], off
	v_lshl_add_u64 v[210:211], v[52:53], 0, s[10:11]
	global_load_dword v186, v[210:211], off
	s_add_u32 s20, s20, 0x18000
	s_addc_u32 s21, s21, 0
	ds_read_b128 v[66:69], v65 offset:4096
	ds_read_b128 v[70:73], v65 offset:8192
	ds_read_b128 v[74:77], v65 offset:12288
	ds_read_b128 v[78:81], v65 offset:16384
	ds_read_b128 v[82:85], v65 offset:20480
	ds_read_b128 v[86:89], v65 offset:24576
	ds_read_b128 v[90:93], v65 offset:28672
	ds_read_b128 v[94:97], v65
	ds_read_b128 v[98:101], v65 offset:32768
	s_waitcnt lgkmcnt(7)
	v_mov_b32_e32 v110, v70
	v_mov_b32_e32 v111, v66
	s_waitcnt lgkmcnt(5)
	v_mov_b32_e32 v112, v78
	v_mov_b32_e32 v113, v74
	s_waitcnt lgkmcnt(3)
	v_mov_b32_e32 v114, v86
	v_mov_b32_e32 v115, v82
	s_waitcnt lgkmcnt(0)
	v_mov_b32_e32 v116, v98
	v_mov_b32_e32 v117, v90
	v_mov_b32_e32 v66, v71
	v_mov_b32_e32 v74, v79
	v_mov_b32_e32 v82, v87
	v_mov_b32_e32 v90, v99
	v_mov_b32_e32 v70, v72
	v_mov_b32_e32 v71, v68
	v_mov_b32_e32 v78, v80
	v_mov_b32_e32 v79, v76
	v_mov_b32_e32 v68, v73
	v_mov_b32_e32 v72, v88
	v_mov_b32_e32 v73, v84
	v_mov_b32_e32 v86, v100
	v_mov_b32_e32 v87, v92
	v_mov_b32_e32 v76, v81
	v_mov_b32_e32 v84, v89
	v_mov_b32_e32 v92, v101
	v_add_u32_e32 v65, 16, v65
	s_waitcnt vmcnt(28)
; __device__ void phase_prep(const Params& p, LAS unsigned char* lds) {
;     ...
;             for (int dd = 0; dd < 128; ++dd) { const float wv = w[(size_t)dd * 6144];
; #pragma unroll
;                 for (int r = 0; r < 9; ++r) acc[r] += s[r * 1024 + dg * 128 + dd] * wv; }
; #pragma unroll
;             for (int r = 0; r < 9; ++r) red[(dg * 9 + r) * 64 + col] = acc[r];
;             __syncthreads();
;             for (int i = tid; i < 9 * 64; i += 512) { const int r = i >> 6, c = i & 63; float a = 0.f;
; #pragma unroll
;                 for (int g = 0; g < 8; ++g) a += red[(g * 9 + r) * 64 + c];
;                 ((float*)(p.ws + WS_ADA))[((size_t)l * 9 + r) * 6144 + e0 + c] = a + p.in[5][l * 6144 + e0 + c]; }
	v_fmac_f32_e32 v64, v188, v94
	v_pk_fma_f32 v[60:61], v[188:189], v[110:111], v[60:61] op_sel_hi:[0,1,1]
	v_pk_fma_f32 v[58:59], v[188:189], v[112:113], v[58:59] op_sel_hi:[0,1,1]
	v_pk_fma_f32 v[56:57], v[188:189], v[114:115], v[56:57] op_sel_hi:[0,1,1]
	v_pk_fma_f32 v[54:55], v[188:189], v[116:117], v[54:55] op_sel_hi:[0,1,1]
	v_fmac_f32_e32 v64, v190, v95
	v_pk_fma_f32 v[60:61], v[190:191], v[66:67], v[60:61] op_sel_hi:[0,1,1]
	v_pk_fma_f32 v[58:59], v[190:191], v[74:75], v[58:59] op_sel_hi:[0,1,1]
	v_pk_fma_f32 v[56:57], v[190:191], v[82:83], v[56:57] op_sel_hi:[0,1,1]
	v_pk_fma_f32 v[54:55], v[190:191], v[90:91], v[54:55] op_sel_hi:[0,1,1]
	v_fmac_f32_e32 v64, v192, v96
	v_pk_fma_f32 v[60:61], v[192:193], v[70:71], v[60:61] op_sel_hi:[0,1,1]
	v_pk_fma_f32 v[58:59], v[192:193], v[78:79], v[58:59] op_sel_hi:[0,1,1]
	v_pk_fma_f32 v[56:57], v[192:193], v[72:73], v[56:57] op_sel_hi:[0,1,1]
	v_pk_fma_f32 v[54:55], v[192:193], v[86:87], v[54:55] op_sel_hi:[0,1,1]
	v_fmac_f32_e32 v64, v194, v97
	v_pk_fma_f32 v[60:61], v[194:195], v[68:69], v[60:61] op_sel_hi:[0,1,1]
	v_pk_fma_f32 v[58:59], v[194:195], v[76:77], v[58:59] op_sel_hi:[0,1,1]
	v_pk_fma_f32 v[56:57], v[194:195], v[84:85], v[56:57] op_sel_hi:[0,1,1]
	v_pk_fma_f32 v[54:55], v[194:195], v[92:93], v[54:55] op_sel_hi:[0,1,1]
	s_add_u32 s2, s20, 0xa8000
	s_min_u32 s2, s2, 0x2e8000
	s_add_u32 s4, s2, 0x6000
	s_add_u32 s6, s2, 0xc000
	s_add_u32 s10, s2, 0x12000
	v_lshl_add_u64 v[204:205], v[52:53], 0, s[2:3]
	global_load_dword v188, v[204:205], off
	v_lshl_add_u64 v[206:207], v[52:53], 0, s[4:5]
	global_load_dword v190, v[206:207], off
	v_lshl_add_u64 v[208:209], v[52:53], 0, s[6:7]
	global_load_dword v192, v[208:209], off
	v_lshl_add_u64 v[210:211], v[52:53], 0, s[10:11]
	global_load_dword v194, v[210:211], off
	s_add_u32 s20, s20, 0x18000
	s_addc_u32 s21, s21, 0
	ds_read_b128 v[66:69], v65 offset:4096
	ds_read_b128 v[70:73], v65 offset:8192
	ds_read_b128 v[74:77], v65 offset:12288
	ds_read_b128 v[78:81], v65 offset:16384
	ds_read_b128 v[82:85], v65 offset:20480
	ds_read_b128 v[86:89], v65 offset:24576
	ds_read_b128 v[90:93], v65 offset:28672
	ds_read_b128 v[94:97], v65
	ds_read_b128 v[98:101], v65 offset:32768
	s_waitcnt lgkmcnt(7)
	v_mov_b32_e32 v110, v70
	v_mov_b32_e32 v111, v66
	s_waitcnt lgkmcnt(5)
	v_mov_b32_e32 v112, v78
	v_mov_b32_e32 v113, v74
	s_waitcnt lgkmcnt(3)
	v_mov_b32_e32 v114, v86
	v_mov_b32_e32 v115, v82
	s_waitcnt lgkmcnt(0)
	v_mov_b32_e32 v116, v98
	v_mov_b32_e32 v117, v90
	v_mov_b32_e32 v66, v71
	v_mov_b32_e32 v74, v79
	v_mov_b32_e32 v82, v87
	v_mov_b32_e32 v90, v99
	v_mov_b32_e32 v70, v72
	v_mov_b32_e32 v71, v68
	v_mov_b32_e32 v78, v80
	v_mov_b32_e32 v79, v76
	v_mov_b32_e32 v68, v73
	v_mov_b32_e32 v72, v88
	v_mov_b32_e32 v73, v84
	v_mov_b32_e32 v86, v100
	v_mov_b32_e32 v87, v92
	v_mov_b32_e32 v76, v81
	v_mov_b32_e32 v84, v89
	v_mov_b32_e32 v92, v101
	v_add_u32_e32 v65, 16, v65
	s_waitcnt vmcnt(28)
	v_fmac_f32_e32 v64, v196, v94
	v_pk_fma_f32 v[60:61], v[196:197], v[110:111], v[60:61] op_sel_hi:[0,1,1]
	v_pk_fma_f32 v[58:59], v[196:197], v[112:113], v[58:59] op_sel_hi:[0,1,1]
	v_pk_fma_f32 v[56:57], v[196:197], v[114:115], v[56:57] op_sel_hi:[0,1,1]
	v_pk_fma_f32 v[54:55], v[196:197], v[116:117], v[54:55] op_sel_hi:[0,1,1]
	v_fmac_f32_e32 v64, v198, v95
	v_pk_fma_f32 v[60:61], v[198:199], v[66:67], v[60:61] op_sel_hi:[0,1,1]
	v_pk_fma_f32 v[58:59], v[198:199], v[74:75], v[58:59] op_sel_hi:[0,1,1]
	v_pk_fma_f32 v[56:57], v[198:199], v[82:83], v[56:57] op_sel_hi:[0,1,1]
	v_pk_fma_f32 v[54:55], v[198:199], v[90:91], v[54:55] op_sel_hi:[0,1,1]
	v_fmac_f32_e32 v64, v200, v96
	v_pk_fma_f32 v[60:61], v[200:201], v[70:71], v[60:61] op_sel_hi:[0,1,1]
	v_pk_fma_f32 v[58:59], v[200:201], v[78:79], v[58:59] op_sel_hi:[0,1,1]
	v_pk_fma_f32 v[56:57], v[200:201], v[72:73], v[56:57] op_sel_hi:[0,1,1]
	v_pk_fma_f32 v[54:55], v[200:201], v[86:87], v[54:55] op_sel_hi:[0,1,1]
	v_fmac_f32_e32 v64, v202, v97
	v_pk_fma_f32 v[60:61], v[202:203], v[68:69], v[60:61] op_sel_hi:[0,1,1]
	v_pk_fma_f32 v[58:59], v[202:203], v[76:77], v[58:59] op_sel_hi:[0,1,1]
	v_pk_fma_f32 v[56:57], v[202:203], v[84:85], v[56:57] op_sel_hi:[0,1,1]
	v_pk_fma_f32 v[54:55], v[202:203], v[92:93], v[54:55] op_sel_hi:[0,1,1]
	s_add_u32 s2, s20, 0xa8000
	s_min_u32 s2, s2, 0x2e8000
	s_add_u32 s4, s2, 0x6000
	s_add_u32 s6, s2, 0xc000
	s_add_u32 s10, s2, 0x12000
	v_lshl_add_u64 v[204:205], v[52:53], 0, s[2:3]
	global_load_dword v196, v[204:205], off
	v_lshl_add_u64 v[206:207], v[52:53], 0, s[4:5]
	global_load_dword v198, v[206:207], off
	v_lshl_add_u64 v[208:209], v[52:53], 0, s[6:7]
	global_load_dword v200, v[208:209], off
	v_lshl_add_u64 v[210:211], v[52:53], 0, s[10:11]
	global_load_dword v202, v[210:211], off
	s_cmp_lg_u32 s20, 0x300000
	s_cbranch_scc1 .LBB0_24
	s_waitcnt vmcnt(0)
	ds_write2st64_b32 v3, v64, v61 offset0:144 offset1:145
	ds_write2st64_b32 v3, v60, v59 offset0:146 offset1:147
	ds_write2st64_b32 v3, v58, v57 offset0:148 offset1:149
	ds_write2st64_b32 v3, v56, v55 offset0:150 offset1:151
	ds_write_b32 v3, v54 offset:38912
	s_waitcnt lgkmcnt(0)
	s_barrier
	s_and_saveexec_b64 s[20:21], s[38:39]
	s_cbranch_execz .LBB0_7
	s_mul_i32 s0, s18, 0x1800
	s_add_i32 s0, s0, s16
	v_or_b32_e32 v52, s0, v6
	v_readlane_b32 s0, v244, 2
	v_ashrrev_i32_e32 v53, 31, v52
	v_readlane_b32 s10, v244, 12
	v_readlane_b32 s11, v244, 13
	s_mul_hi_i32 s19, s18, 9
	s_mul_i32 s18, s18, 9
	v_lshl_add_u64 v[52:53], v[52:53], 2, s[10:11]
	v_lshl_add_u64 v[54:55], s[16:17], 2, v[12:13]
	s_mov_b64 s[16:17], 0
	v_mov_b32_e32 v56, v2
	v_readlane_b32 s1, v244, 3
	v_readlane_b32 s2, v244, 4
	v_readlane_b32 s3, v244, 5
	v_readlane_b32 s4, v244, 6
	v_readlane_b32 s5, v244, 7
	v_readlane_b32 s6, v244, 8
	v_readlane_b32 s7, v244, 9
	v_readlane_b32 s8, v244, 10
	v_readlane_b32 s9, v244, 11
	v_readlane_b32 s12, v244, 14
	v_readlane_b32 s13, v244, 15
	v_readlane_b32 s14, v244, 16
	v_readlane_b32 s15, v244, 17
